# neighbourhood-attention item rewritten by hand: bias/mask tables per lane, only potentially-valid score columns exponentiated, no running max when runtime bounds hold (fallback to original path otherw
# speedup vs baseline: 1.0898x; 1.0238x over previous
; DI int get_tid() { int t = threadIdx.x; asm volatile("" : "+v"(t)); return t; }
; template <bool NA, bool TRACK>
; DI void attn_item(char* lds, const bf16_t* P, bf16_t* Y, const bf16_t* vt, int rp, int q_off, int k1_off, int nt1,
;                   int vk1, int k2_off, int nt2, int vk2, int g_off, int y_off, int rlo, const float* rpb) {
;   asm volatile("" : "+v"(q_off), "+v"(g_off), "+v"(y_off));
;   const bf16_t* qp = P + q_off;
;   const bf16_t* kp1 = P + k1_off;
;   const bf16_t* kp2 = P + k2_off;
;   const int tid = get_tid(), lane = tid & 63, w = tid >> 6, r = lane & 31, h = lane >> 5;
;   const int lr = tid >> 3, lc = tid & 7;
;   const int nt = nt1 + nt2;
;   const int woff = lr * 128 + ((lc ^ ((lr >> 1) & 7)) << 4);
;   const int swz = (r >> 1) & 7;
;   float* tab = (float*)(lds + 131072);
;   int rw = 0, r0w = 0, cq = 0, c0 = 0;
;   if (NA) {
;     rw = rp * 4 + (w >> 1);
;     r0w = clampi(rw - 4, 0, 24);
;     cq = (w & 1) * 32 + r;
;     c0 = clampi(cq - 8, 0, 48);
;     for (int e = tid; e < 15 * 128; e += NTHREADS) {
;       const int dr = e >> 7, dc = (e & 127) - 48;
;       tab[e] = (dc >= 0 && dc < 31) ? rpb[dr * 31 + dc] * LOG2E : 0.f;
;     }
;   }
;   bf16x8 qf[4];
; #pragma unroll
;   for (int ks = 0; ks < 4; ++ks) qf[ks] = *(const bf16x8*)(qp + (size_t)(w * 32 + r) * INW + ks * 16 + h * 8);
;   u32x2 gate[2][4];
; #pragma unroll
;   for (int dm = 0; dm < 2; ++dm)
; #pragma unroll
;     for (int g = 0; g < 4; ++g)
;       gate[dm][g] = *(const u32x2*)(P + g_off + (size_t)(w * 32 + r) * INW + dm * 32 + 8 * g + 4 * h);
; #pragma unroll
;   for (int ks = 0; ks < 4; ++ks) asm volatile("" : "+v"(qf[ks]));
; #pragma unroll
;   for (int dm = 0; dm < 2; ++dm)
; #pragma unroll
;     for (int g = 0; g < 4; ++g) asm volatile("" : "+v"(gate[dm][g]));
;   f32x16 o[2];
;   o[0] = zero16(); o[1] = zero16();
;   f32x16 negm;
; #pragma unroll
;   for (int i = 0; i < 16; ++i) negm[i] = 0.f;
;   float l_run = 0.f;
;   constexpr int TPI = 4;
;   const int niter = (nt + TPI - 1) / TPI;
;   u32x4 rk[TPI], rv[TPI];
.LBB0_185:
	v_readlane_b32 s2, v255, 10
	v_readlane_b32 s3, v255, 11
	s_nop 3
	s_cmp_eq_u64 s[2:3], 0
	s_cbranch_scc1 .Lna_orig
	v_readlane_b32 s0, v255, 12
	v_readlane_b32 s46, v254, 37
	v_readlane_b32 s47, v254, 38
	s_nop 3
	s_add_i32 s0, s25, s0
	s_mul_i32 s0, s0, 0x744
	s_add_u32 s46, s46, s0
	s_addc_u32 s47, s47, 0
	v_and_b32_e32 v0, 0x7f, v251
	v_subrev_u32_e32 v0, 48, v0
	v_cmp_gt_u32_e32 vcc, 31, v0
	v_med3_i32 v0, v0, 0, 30
	v_lshrrev_b32_e32 v162, 7, v251
	v_mul_u32_u24_e32 v163, 31, v162
	v_add_lshl_u32 v163, v163, v0, 2
	global_load_dword v130, v163, s[46:47]
	global_load_dword v134, v163, s[46:47] offset:496
	global_load_dword v138, v163, s[46:47] offset:992
	v_min_u32_e32 v162, 2, v162
	v_mul_u32_u24_e32 v162, 31, v162
	v_add_lshl_u32 v162, v162, v0, 2
	global_load_dword v142, v162, s[46:47] offset:1488
	v_readlane_b32 s44, v254, 49
	v_readlane_b32 s45, v254, 50
	s_ashr_i32 s13, s12, 31
	s_ashr_i32 s11, s10, 31
	s_mov_b32 s34, s26
	s_ashr_i32 s35, s26, 31
	s_lshl_b64 s[34:35], s[34:35], 1
	s_add_u32 s34, s34, s44
	s_addc_u32 s35, s35, s45
	s_mov_b32 s36, s27
	s_ashr_i32 s37, s27, 31
	s_lshl_b64 s[36:37], s[36:37], 1
	s_add_u32 s36, s36, s44
	s_addc_u32 s37, s37, s45
	s_lshl_b64 s[4:5], s[12:13], 1
	s_add_u32 s4, s4, s44
	s_addc_u32 s5, s5, s45
	s_lshl_b64 s[6:7], s[10:11], 1
	s_add_u32 s6, s6, s44
	s_addc_u32 s7, s7, s45
	s_add_i32 s30, s79, 4
	s_add_i32 s19, s30, 3
	s_lshr_b32 s19, s19, 2
	s_mov_b32 s18, 0
	v_bfe_u32 v183, v251, 5, 1
	v_ashrrev_i32_e32 v0, 1, v251
	s_movk_i32 s0, 0xffe0
	v_bfi_b32 v182, s0, v0, v251
	v_lshlrev_b32_e32 v174, 3, v183
	v_mov_b32_e32 v172, s28
	v_mul_u32_u24_e32 v0, 0x1600, v182
	v_lshl_add_u32 v204, v183, 4, v0
	v_lshl_add_u32 v205, v183, 3, v0
	v_lshrrev_b32_e32 v0, 3, v251
	v_and_b32_e32 v162, 7, v251
	v_mul_u32_u24_e32 v200, 0x1600, v0
	v_lshl_add_u32 v200, v162, 4, v200
	v_mul_u32_u24_e32 v201, 0x1200, v0
	v_lshl_add_u32 v201, v162, 4, v201
	global_load_dwordx4 v[66:69], v204, s[34:35]
	global_load_dwordx4 v[70:73], v204, s[34:35] offset:32
	global_load_dwordx4 v[74:77], v204, s[34:35] offset:64
	global_load_dwordx4 v[78:81], v204, s[34:35] offset:96
	s_waitcnt vmcnt(4)
	v_lshlrev_b32_e32 v163, 2, v251
	v_add_u32_e32 v163, 0x20000, v163
	v_mov_b32_e32 v146, 0
	v_mul_f32_e32 v130, 0x3fb8aa3b, v130
	v_cndmask_b32_e32 v130, 0, v130, vcc
	v_max_f32_e64 v146, v146, |v130|
	v_mul_f32_e32 v134, 0x3fb8aa3b, v134
	v_cndmask_b32_e32 v134, 0, v134, vcc
	v_max_f32_e64 v146, v146, |v134|
	v_mul_f32_e32 v138, 0x3fb8aa3b, v138
	v_cndmask_b32_e32 v138, 0, v138, vcc
	v_max_f32_e64 v146, v146, |v138|
	v_mul_f32_e32 v142, 0x3fb8aa3b, v142
	v_cndmask_b32_e32 v142, 0, v142, vcc
	v_max_f32_e64 v146, v146, |v142|
	ds_write_b32 v163, v130
	ds_write_b32 v163, v134 offset:2048
	ds_write_b32 v163, v138 offset:4096
	s_movk_i32 s0, 0x180
	v_cmp_gt_u32_e64 s[2:3], s0, v251
	s_nop 3
	s_and_saveexec_b64 s[14:15], s[2:3]
	ds_write_b32 v163, v142 offset:6144
	s_mov_b64 exec, s[14:15]
	s_mov_b32 s0, 0x41c00000
	v_cmp_lt_f32_e32 vcc, s0, v146
	s_nop 4
	s_cmp_lg_u64 vcc, 0
	s_cselect_b32 s0, 1, 0
	v_mov_b32_e32 v146, s0
	v_lshrrev_b32_e32 v163, 6, v251
	v_lshlrev_b32_e32 v163, 2, v163
	v_add_u32_e32 v163, 0x1ffe0, v163
	ds_write_b32 v163, v146
	s_mov_b32 s31, 0
	s_cmp_lt_i32 s31, s79
	s_cselect_b32 s21, 0, s79
	s_cselect_b32 s22, s4, s6
	s_cselect_b32 s23, s5, s7
	s_cselect_b32 s29, s90, 0x800
	s_sub_i32 s20, s31, s21
	s_mul_i32 s21, s20, 0x58000
	s_add_u32 s14, s22, s21
	s_addc_u32 s15, s23, 0
	s_lshl_b32 s20, s20, 6
	s_add_i32 s20, s20, s29
	s_lshl_b32 s20, s20, 1
	s_add_u32 s16, s8, s20
	s_addc_u32 s17, s9, 0
	global_load_dwordx4 v[130:133], v200, s[14:15]
	global_load_dwordx4 v[134:137], v201, s[16:17]
	s_mov_b32 s31, 1
	s_cmp_lt_i32 s31, s79
	s_cselect_b32 s21, 0, s79
	s_cselect_b32 s22, s4, s6
	s_cselect_b32 s23, s5, s7
	s_cselect_b32 s29, s90, 0x800
	s_sub_i32 s20, s31, s21
	s_mul_i32 s21, s20, 0x58000
	s_add_u32 s14, s22, s21
	s_addc_u32 s15, s23, 0
	s_lshl_b32 s20, s20, 6
	s_add_i32 s20, s20, s29
	s_lshl_b32 s20, s20, 1
	s_add_u32 s16, s8, s20
	s_addc_u32 s17, s9, 0
	global_load_dwordx4 v[138:141], v200, s[14:15]
	global_load_dwordx4 v[142:145], v201, s[16:17]
	s_mov_b32 s31, 2
	s_cmp_lt_i32 s31, s79
	s_cselect_b32 s21, 0, s79
	s_cselect_b32 s22, s4, s6
	s_cselect_b32 s23, s5, s7
	s_cselect_b32 s29, s90, 0x800
	s_sub_i32 s20, s31, s21
	s_mul_i32 s21, s20, 0x58000
	s_add_u32 s14, s22, s21
	s_addc_u32 s15, s23, 0
	s_lshl_b32 s20, s20, 6
	s_add_i32 s20, s20, s29
	s_lshl_b32 s20, s20, 1
	s_add_u32 s16, s8, s20
	s_addc_u32 s17, s9, 0
	global_load_dwordx4 v[146:149], v200, s[14:15]
	global_load_dwordx4 v[150:153], v201, s[16:17]
	s_mov_b32 s31, 3
	s_cmp_lt_i32 s31, s79
	s_cselect_b32 s21, 0, s79
	s_cselect_b32 s22, s4, s6
	s_cselect_b32 s23, s5, s7
	s_cselect_b32 s29, s90, 0x800
	s_sub_i32 s20, s31, s21
	s_mul_i32 s21, s20, 0x58000
	s_add_u32 s14, s22, s21
	s_addc_u32 s15, s23, 0
	s_lshl_b32 s20, s20, 6
	s_add_i32 s20, s20, s29
	s_lshl_b32 s20, s20, 1
	s_add_u32 s16, s8, s20
	s_addc_u32 s17, s9, 0
	global_load_dwordx4 v[154:157], v200, s[14:15]
	global_load_dwordx4 v[158:161], v201, s[16:17]
	global_load_dwordx2 v[184:185], v205, s[36:37]
	global_load_dwordx2 v[180:181], v205, s[36:37] offset:16
	global_load_dwordx2 v[178:179], v205, s[36:37] offset:32
	global_load_dwordx2 v[176:177], v205, s[36:37] offset:48
	global_load_dwordx2 v[170:171], v205, s[36:37] offset:64
	global_load_dwordx2 v[168:169], v205, s[36:37] offset:80
	global_load_dwordx2 v[166:167], v205, s[36:37] offset:96
	global_load_dwordx2 v[164:165], v205, s[36:37] offset:112
	v_lshlrev_b32_e32 v162, 4, v251
	v_xor_b32_e32 v162, v162, v251
	v_and_b32_e32 v162, 0x70, v162
; DI int get_tid() { int t = threadIdx.x; asm volatile("" : "+v"(t)); return t; }
; template <bool NA, bool TRACK>
; DI void attn_item(char* lds, const bf16_t* P, bf16_t* Y, const bf16_t* vt, int rp, int q_off, int k1_off, int nt1,
;                   int vk1, int k2_off, int nt2, int vk2, int g_off, int y_off, int rlo, const float* rpb) {
;     ...
;   const int tid = get_tid(), lane = tid & 63, w = tid >> 6, r = lane & 31, h = lane >> 5;
;   const int lr = tid >> 3, lc = tid & 7;
;   const int nt = nt1 + nt2;
;   const int woff = lr * 128 + ((lc ^ ((lr >> 1) & 7)) << 4);
;   const int swz = (r >> 1) & 7;
;   float* tab = (float*)(lds + 131072);
;   int rw = 0, r0w = 0, cq = 0, c0 = 0;
;   if (NA) {
;     rw = rp * 4 + (w >> 1);
;     r0w = clampi(rw - 4, 0, 24);
;     cq = (w & 1) * 32 + r;
;     c0 = clampi(cq - 8, 0, 48);
;     for (int e = tid; e < 15 * 128; e += NTHREADS) {
;       const int dr = e >> 7, dc = (e & 127) - 48;
;       tab[e] = (dc >= 0 && dc < 31) ? rpb[dr * 31 + dc] * LOG2E : 0.f;
;     }
;   }
;   bf16x8 qf[4];
; #pragma unroll
;   for (int ks = 0; ks < 4; ++ks) qf[ks] = *(const bf16x8*)(qp + (size_t)(w * 32 + r) * INW + ks * 16 + h * 8);
;   u32x2 gate[2][4];
; #pragma unroll
;   for (int dm = 0; dm < 2; ++dm)
; #pragma unroll
;     for (int g = 0; g < 4; ++g)
;       gate[dm][g] = *(const u32x2*)(P + g_off + (size_t)(w * 32 + r) * INW + dm * 32 + 8 * g + 4 * h);
; #pragma unroll
;   for (int ks = 0; ks < 4; ++ks) asm volatile("" : "+v"(qf[ks]));
; #pragma unroll
;   for (int dm = 0; dm < 2; ++dm)
; #pragma unroll
;     for (int g = 0; g < 4; ++g) asm volatile("" : "+v"(gate[dm][g]));
;   f32x16 o[2];
;   o[0] = zero16(); o[1] = zero16();
;   f32x16 negm;
; #pragma unroll
;   for (int i = 0; i < 16; ++i) negm[i] = 0.f;
;   float l_run = 0.f;
;     ...
;         if (NA) {
;           if (t < nt1) {
;             const float* trow = tab + drow * 128 + 63 - cq;
; #pragma unroll
;             for (int kt = 0; kt < 2; ++kt)
; #pragma unroll
;               for (int i = 0; i < 16; ++i) {
;                 const int kc = kt * 32 + (i & 3) + 8 * (i >> 2) + 4 * h;
;                 const bool ok = (unsigned)(kc - c0) < 16u;
;                 const float t2 = s[kt][i] + trow[kc];
;                 s[kt][i] = ok ? t2 : -1e30f;
;               }
;           }
	v_lshl_or_b32 v199, v0, 7, v162
	v_and_b32_e32 v0, 31, v251
	v_lshlrev_b32_e32 v0, 7, v0
	v_bfe_u32 v162, v251, 1, 3
	v_xor_b32_e32 v162, v162, v183
	v_lshl_or_b32 v191, v162, 4, v0
	v_xor_b32_e32 v163, 2, v162
	v_lshl_or_b32 v192, v163, 4, v0
	v_xor_b32_e32 v163, 4, v162
	v_lshl_or_b32 v193, v163, 4, v0
	v_xor_b32_e32 v163, 6, v162
	v_lshl_or_b32 v194, v163, 4, v0
	v_mov_b32_e32 v2, 0
	v_mov_b32_e32 v3, 0
	v_mov_b32_e32 v4, 0
	v_mov_b32_e32 v5, 0
	v_mov_b32_e32 v6, 0
	v_mov_b32_e32 v7, 0
	v_mov_b32_e32 v8, 0
	v_mov_b32_e32 v9, 0
	v_mov_b32_e32 v10, 0
	v_mov_b32_e32 v11, 0
	v_mov_b32_e32 v12, 0
	v_mov_b32_e32 v13, 0
	v_mov_b32_e32 v14, 0
	v_mov_b32_e32 v15, 0
	v_mov_b32_e32 v16, 0
	v_mov_b32_e32 v17, 0
	v_mov_b32_e32 v18, 0
	v_mov_b32_e32 v19, 0
	v_mov_b32_e32 v20, 0
	v_mov_b32_e32 v21, 0
	v_mov_b32_e32 v22, 0
	v_mov_b32_e32 v23, 0
	v_mov_b32_e32 v24, 0
	v_mov_b32_e32 v25, 0
	v_mov_b32_e32 v26, 0
	v_mov_b32_e32 v27, 0
	v_mov_b32_e32 v28, 0
	v_mov_b32_e32 v29, 0
	v_mov_b32_e32 v30, 0
	v_mov_b32_e32 v31, 0
	v_mov_b32_e32 v32, 0
	v_mov_b32_e32 v33, 0
	v_mov_b32_e32 v186, 0
	v_mov_b32_e32 v187, 0
	v_mov_b32_e32 v188, 0
	v_mov_b32_e32 v189, 0
	v_mov_b32_e32 v114, 0
	v_mov_b32_e32 v115, 0
	v_mov_b32_e32 v116, 0
	v_mov_b32_e32 v117, 0
	v_mov_b32_e32 v118, 0
	v_mov_b32_e32 v119, 0
	v_mov_b32_e32 v120, 0
	v_mov_b32_e32 v121, 0
	v_mov_b32_e32 v122, 0
	v_mov_b32_e32 v123, 0
	v_mov_b32_e32 v124, 0
	v_mov_b32_e32 v125, 0
	v_mov_b32_e32 v126, 0
	v_mov_b32_e32 v127, 0
	v_mov_b32_e32 v128, 0
	v_mov_b32_e32 v129, 0
	v_lshrrev_b32_e32 v0, 6, v251
	s_nop 0
	v_readfirstlane_b32 s39, v0
	s_nop 3
	s_lshr_b32 s38, s39, 1
	s_add_i32 s38, s38, s24
	s_sub_i32 s40, s89, s38
	s_add_i32 s40, s40, 7
	s_sub_i32 s38, s38, 4
	s_max_i32 s38, s38, 0
	s_min_i32 s38, s38, 24
	s_sub_i32 s38, s38, s89
	s_and_b32 s39, s39, 1
	v_and_b32_e32 v0, 31, v251
	s_lshl_b32 s0, s39, 5
	v_add_u32_e32 v0, s0, v0
	v_subrev_u32_e32 v162, 8, v0
	v_med3_i32 v162, v162, 0, 48
	v_lshlrev_b32_e32 v163, 2, v183
	v_sub_u32_e32 v162, v163, v162
	v_sub_u32_e32 v0, v163, v0
	v_add_u32_e32 v0, 63, v0
	v_lshlrev_b32_e32 v202, 2, v0
	v_add_u32_e32 v202, 0x20000, v202
	s_cmp_eq_u32 s39, 0
	s_cbranch_scc0 .Lna_mask1
	v_add_u32_e32 v163, 0, v162
	v_cmp_gt_u32_e32 vcc, 16, v163
	s_nop 1
	v_cndmask_b32_e32 v206, v249, v250, vcc
	v_add_u32_e32 v163, 1, v162
	v_cmp_gt_u32_e32 vcc, 16, v163
	s_nop 1
	v_cndmask_b32_e32 v207, v249, v250, vcc
	v_add_u32_e32 v163, 2, v162
	v_cmp_gt_u32_e32 vcc, 16, v163
	s_nop 1
	v_cndmask_b32_e32 v208, v249, v250, vcc
	v_add_u32_e32 v163, 3, v162
	v_cmp_gt_u32_e32 vcc, 16, v163
	s_nop 1
	v_cndmask_b32_e32 v209, v249, v250, vcc
	v_add_u32_e32 v163, 8, v162
	v_cmp_gt_u32_e32 vcc, 16, v163
	s_nop 1
	v_cndmask_b32_e32 v210, v249, v250, vcc
	v_add_u32_e32 v163, 9, v162
	v_cmp_gt_u32_e32 vcc, 16, v163
	s_nop 1
	v_cndmask_b32_e32 v211, v249, v250, vcc
	v_add_u32_e32 v163, 10, v162
	v_cmp_gt_u32_e32 vcc, 16, v163
	s_nop 1
	v_cndmask_b32_e32 v212, v249, v250, vcc
	v_add_u32_e32 v163, 11, v162
	v_cmp_gt_u32_e32 vcc, 16, v163
	s_nop 1
	v_cndmask_b32_e32 v213, v249, v250, vcc
	v_add_u32_e32 v163, 16, v162
	v_cmp_gt_u32_e32 vcc, 16, v163
	s_nop 1
	v_cndmask_b32_e32 v214, v249, v250, vcc
	v_add_u32_e32 v163, 17, v162
	v_cmp_gt_u32_e32 vcc, 16, v163
	s_nop 1
	v_cndmask_b32_e32 v215, v249, v250, vcc
	v_add_u32_e32 v163, 18, v162
	v_cmp_gt_u32_e32 vcc, 16, v163
	s_nop 1
	v_cndmask_b32_e32 v216, v249, v250, vcc
	v_add_u32_e32 v163, 19, v162
	v_cmp_gt_u32_e32 vcc, 16, v163
	s_nop 1
	v_cndmask_b32_e32 v217, v249, v250, vcc
	v_add_u32_e32 v163, 24, v162
	v_cmp_gt_u32_e32 vcc, 16, v163
	s_nop 1
	v_cndmask_b32_e32 v218, v249, v250, vcc
	v_add_u32_e32 v163, 25, v162
	v_cmp_gt_u32_e32 vcc, 16, v163
	s_nop 1
	v_cndmask_b32_e32 v219, v249, v250, vcc
	v_add_u32_e32 v163, 26, v162
	v_cmp_gt_u32_e32 vcc, 16, v163
	s_nop 1
	v_cndmask_b32_e32 v220, v249, v250, vcc
	v_add_u32_e32 v163, 27, v162
	v_cmp_gt_u32_e32 vcc, 16, v163
	s_nop 1
	v_cndmask_b32_e32 v221, v249, v250, vcc
	v_add_u32_e32 v163, 32, v162
	v_cmp_gt_u32_e32 vcc, 16, v163
	s_nop 1
	v_cndmask_b32_e32 v222, v249, v250, vcc
	v_add_u32_e32 v163, 33, v162
	v_cmp_gt_u32_e32 vcc, 16, v163
	s_nop 1
	v_cndmask_b32_e32 v223, v249, v250, vcc
	v_add_u32_e32 v163, 34, v162
	v_cmp_gt_u32_e32 vcc, 16, v163
	s_nop 1
	v_cndmask_b32_e32 v224, v249, v250, vcc
	v_add_u32_e32 v163, 35, v162
	v_cmp_gt_u32_e32 vcc, 16, v163
	s_nop 1
	v_cndmask_b32_e32 v225, v249, v250, vcc
	s_branch .Lna_maskd
.Lna_mask1:
	v_add_u32_e32 v163, 24, v162
	v_cmp_gt_u32_e32 vcc, 16, v163
	s_nop 1
	v_cndmask_b32_e32 v206, v249, v250, vcc
	v_add_u32_e32 v163, 25, v162
	v_cmp_gt_u32_e32 vcc, 16, v163
	s_nop 1
	v_cndmask_b32_e32 v207, v249, v250, vcc
	v_add_u32_e32 v163, 26, v162
	v_cmp_gt_u32_e32 vcc, 16, v163
	s_nop 1
	v_cndmask_b32_e32 v208, v249, v250, vcc
	v_add_u32_e32 v163, 27, v162
	v_cmp_gt_u32_e32 vcc, 16, v163
	s_nop 1
	v_cndmask_b32_e32 v209, v249, v250, vcc
	v_add_u32_e32 v163, 32, v162
	v_cmp_gt_u32_e32 vcc, 16, v163
	s_nop 1
	v_cndmask_b32_e32 v210, v249, v250, vcc
	v_add_u32_e32 v163, 33, v162
	v_cmp_gt_u32_e32 vcc, 16, v163
	s_nop 1
	v_cndmask_b32_e32 v211, v249, v250, vcc
	v_add_u32_e32 v163, 34, v162
	v_cmp_gt_u32_e32 vcc, 16, v163
	s_nop 1
	v_cndmask_b32_e32 v212, v249, v250, vcc
	v_add_u32_e32 v163, 35, v162
	v_cmp_gt_u32_e32 vcc, 16, v163
	s_nop 1
	v_cndmask_b32_e32 v213, v249, v250, vcc
	v_add_u32_e32 v163, 40, v162
	v_cmp_gt_u32_e32 vcc, 16, v163
	s_nop 1
	v_cndmask_b32_e32 v214, v249, v250, vcc
	v_add_u32_e32 v163, 41, v162
	v_cmp_gt_u32_e32 vcc, 16, v163
	s_nop 1
	v_cndmask_b32_e32 v215, v249, v250, vcc
	v_add_u32_e32 v163, 42, v162
	v_cmp_gt_u32_e32 vcc, 16, v163
	s_nop 1
	v_cndmask_b32_e32 v216, v249, v250, vcc
	v_add_u32_e32 v163, 43, v162
	v_cmp_gt_u32_e32 vcc, 16, v163
	s_nop 1
	v_cndmask_b32_e32 v217, v249, v250, vcc
	v_add_u32_e32 v163, 48, v162
	v_cmp_gt_u32_e32 vcc, 16, v163
	s_nop 1
	v_cndmask_b32_e32 v218, v249, v250, vcc
	v_add_u32_e32 v163, 49, v162
	v_cmp_gt_u32_e32 vcc, 16, v163
	s_nop 1
	v_cndmask_b32_e32 v219, v249, v250, vcc
	v_add_u32_e32 v163, 50, v162
	v_cmp_gt_u32_e32 vcc, 16, v163
	s_nop 1
	v_cndmask_b32_e32 v220, v249, v250, vcc
	v_add_u32_e32 v163, 51, v162
	v_cmp_gt_u32_e32 vcc, 16, v163
	s_nop 1
	v_cndmask_b32_e32 v221, v249, v250, vcc
	v_add_u32_e32 v163, 56, v162
	v_cmp_gt_u32_e32 vcc, 16, v163
	s_nop 1
	v_cndmask_b32_e32 v222, v249, v250, vcc
	v_add_u32_e32 v163, 57, v162
	v_cmp_gt_u32_e32 vcc, 16, v163
	s_nop 1
	v_cndmask_b32_e32 v223, v249, v250, vcc
	v_add_u32_e32 v163, 58, v162
	v_cmp_gt_u32_e32 vcc, 16, v163
	s_nop 1
	v_cndmask_b32_e32 v224, v249, v250, vcc
	v_add_u32_e32 v163, 59, v162
	v_cmp_gt_u32_e32 vcc, 16, v163
	s_nop 1
	v_cndmask_b32_e32 v225, v249, v250, vcc
; DI f32x16 mfma32(bf16x8 a, bf16x8 b, f32x16 c) { return __builtin_amdgcn_mfma_f32_32x32x16_bf16(a, b, c, 0, 0, 0); }
; #define ATT_WRITE(IT, HALF) do { _Pragma("unroll") for (int j_ = 0; j_ < TPI; ++j_) { const int t_ = (IT) * TPI + j_; if (t_ < nt) { \
;       char* sl_ = lds + (HALF) * 65536 + j_ * 16384; \
;       *(u32x4*)(sl_ + woff) = rk[j_]; \
;       *(u32x4*)(sl_ + 8192 + woff) = rv[j_]; } } } while (0)
; template <bool NA, bool TRACK>
; DI void attn_item(char* lds, const bf16_t* P, bf16_t* Y, const bf16_t* vt, int rp, int q_off, int k1_off, int nt1,
;                   int vk1, int k2_off, int nt2, int vk2, int g_off, int y_off, int rlo, const float* rpb) {
;     ...
;   ATT_LOAD(0);
;   ATT_WRITE(0, 0);
;   __syncthreads();
;   for (int it = 0; it < niter; ++it) {
;     const int hb = it & 1;
;     if constexpr (NA || TRACK) { if (it + 1 < niter) ATT_LOAD(it + 1); }
;     ...
;     for (int j = 0; j < TPI; ++j) {
;       const int t = it * TPI + j;
;       if (t >= nt) break;
;       bool active = true;
;       int drow = 0;
;       if (NA && t < nt1) {
;         const int R = rlo + t;
;         active = (R >= r0w) && (R < r0w + 8);
;         drow = R - rw + 7;
;       }
;       if (active) {
;         const char* Ks = lds + hb * 65536 + j * 16384;
;         const char* Vs = Ks + 8192;
;         bf16x8 kf[8];
; #pragma unroll
;         for (int kt = 0; kt < 2; ++kt)
; #pragma unroll
;           for (int ks = 0; ks < 4; ++ks)
;             kf[kt * 4 + ks] = *(const bf16x8*)(Ks + (kt * 32 + r) * 128 + (((2 * ks + h) ^ swz) << 4));
;         __builtin_amdgcn_sched_barrier(0);
;         f32x16 s[2];
;         __builtin_amdgcn_s_setprio(1);
; #pragma unroll
;         for (int kt = 0; kt < 2; ++kt) {
;           s[kt] = mfma32(kf[kt * 4], qf[0], negm);
; #pragma unroll
;           for (int ks = 1; ks < 4; ++ks) s[kt] = mfma32(kf[kt * 4 + ks], qf[ks], s[kt]);
;         }
.Lna_maskd:
	s_waitcnt vmcnt(0)
	ds_write_b128 v199, v[130:133]
	ds_write_b128 v199, v[134:137] offset:8192
	ds_write_b128 v199, v[138:141] offset:16384
	ds_write_b128 v199, v[142:145] offset:24576
	ds_write_b128 v199, v[146:149] offset:32768
	ds_write_b128 v199, v[150:153] offset:40960
	ds_write_b128 v199, v[154:157] offset:49152
	ds_write_b128 v199, v[158:161] offset:57344
	v_xor_b32_e32 v199, 0x10000, v199
	s_waitcnt lgkmcnt(0)
	s_barrier
	v_mov_b32_e32 v0, 0x1ffe0
	ds_read_b128 v[130:133], v0
	ds_read_b128 v[134:137], v0 offset:16
	s_waitcnt lgkmcnt(0)
	v_or3_b32 v130, v130, v131, v132
	v_or3_b32 v134, v134, v135, v136
	v_or3_b32 v130, v130, v133, v137
	v_or_b32_e32 v130, v130, v134
	v_cmp_ne_u32_e32 vcc, 0, v130
	s_nop 3
	s_cmp_lg_u64 vcc, 0
	s_cbranch_scc1 .Lna_orig
.Lna_loop:
	s_lshl_b32 s31, s18, 2
	s_add_i32 s31, s31, 4
	s_cmp_ge_i32 s31, s30
	s_cbranch_scc1 .Lna_ld0
	s_cmp_lt_i32 s31, s79
	s_cselect_b32 s21, 0, s79
	s_cselect_b32 s22, s4, s6
	s_cselect_b32 s23, s5, s7
	s_cselect_b32 s29, s90, 0x800
	s_sub_i32 s20, s31, s21
	s_mul_i32 s21, s20, 0x58000
	s_add_u32 s14, s22, s21
	s_addc_u32 s15, s23, 0
	s_lshl_b32 s20, s20, 6
	s_add_i32 s20, s20, s29
	s_lshl_b32 s20, s20, 1
	s_add_u32 s16, s8, s20
	s_addc_u32 s17, s9, 0
	global_load_dwordx4 v[130:133], v200, s[14:15]
	global_load_dwordx4 v[134:137], v201, s[16:17]
.Lna_ld0:
	s_lshl_b32 s31, s18, 2
	s_add_i32 s31, s31, 5
	s_cmp_ge_i32 s31, s30
	s_cbranch_scc1 .Lna_ld1
	s_cmp_lt_i32 s31, s79
	s_cselect_b32 s21, 0, s79
	s_cselect_b32 s22, s4, s6
	s_cselect_b32 s23, s5, s7
	s_cselect_b32 s29, s90, 0x800
	s_sub_i32 s20, s31, s21
	s_mul_i32 s21, s20, 0x58000
	s_add_u32 s14, s22, s21
	s_addc_u32 s15, s23, 0
	s_lshl_b32 s20, s20, 6
	s_add_i32 s20, s20, s29
	s_lshl_b32 s20, s20, 1
	s_add_u32 s16, s8, s20
	s_addc_u32 s17, s9, 0
	global_load_dwordx4 v[138:141], v200, s[14:15]
	global_load_dwordx4 v[142:145], v201, s[16:17]
.Lna_ld1:
	s_lshl_b32 s31, s18, 2
	s_add_i32 s31, s31, 6
	s_cmp_ge_i32 s31, s30
	s_cbranch_scc1 .Lna_ld2
	s_cmp_lt_i32 s31, s79
	s_cselect_b32 s21, 0, s79
	s_cselect_b32 s22, s4, s6
	s_cselect_b32 s23, s5, s7
	s_cselect_b32 s29, s90, 0x800
	s_sub_i32 s20, s31, s21
	s_mul_i32 s21, s20, 0x58000
	s_add_u32 s14, s22, s21
	s_addc_u32 s15, s23, 0
	s_lshl_b32 s20, s20, 6
	s_add_i32 s20, s20, s29
	s_lshl_b32 s20, s20, 1
	s_add_u32 s16, s8, s20
	s_addc_u32 s17, s9, 0
	global_load_dwordx4 v[146:149], v200, s[14:15]
	global_load_dwordx4 v[150:153], v201, s[16:17]
.Lna_ld2:
	s_lshl_b32 s31, s18, 2
	s_add_i32 s31, s31, 7
	s_cmp_ge_i32 s31, s30
	s_cbranch_scc1 .Lna_ld3
	s_cmp_lt_i32 s31, s79
	s_cselect_b32 s21, 0, s79
	s_cselect_b32 s22, s4, s6
	s_cselect_b32 s23, s5, s7
	s_cselect_b32 s29, s90, 0x800
	s_sub_i32 s20, s31, s21
	s_mul_i32 s21, s20, 0x58000
	s_add_u32 s14, s22, s21
	s_addc_u32 s15, s23, 0
	s_lshl_b32 s20, s20, 6
	s_add_i32 s20, s20, s29
	s_lshl_b32 s20, s20, 1
	s_add_u32 s16, s8, s20
	s_addc_u32 s17, s9, 0
	global_load_dwordx4 v[154:157], v200, s[14:15]
	global_load_dwordx4 v[158:161], v201, s[16:17]
.Lna_ld3:
	s_lshl_b32 s31, s18, 2
	s_add_i32 s41, s31, 4
	s_min_i32 s41, s41, s30
	s_mov_b32 s42, 0
.Lna_tile:
	v_add_u32_e32 v195, s42, v191
	v_add_u32_e32 v196, s42, v192
	v_add_u32_e32 v197, s42, v193
	v_add_u32_e32 v198, s42, v194
	s_cmp_ge_i32 s31, s79
	s_cbranch_scc1 .Lna_ctx
	s_sub_i32 s0, s31, s38
	s_cmp_lt_u32 s0, 8
	s_cbranch_scc0 .Lna_next
	s_add_i32 s0, s40, s31
	s_lshl_b32 s0, s0, 9
	v_add_u32_e32 v203, s0, v202
	s_cmp_eq_u32 s39, 0
	s_cbranch_scc0 .Lna_t1
	ds_read_b128 v[82:85], v195
	ds_read_b128 v[86:89], v196
	ds_read_b128 v[90:93], v197
	ds_read_b128 v[94:97], v198
	ds_read_b128 v[98:101], v195 offset:4096
	ds_read_b128 v[102:105], v196 offset:4096
	ds_read_b128 v[106:109], v197 offset:4096
	ds_read_b128 v[110:113], v198 offset:4096
	ds_read_b32 v226, v203
	ds_read_b32 v227, v203 offset:4
	ds_read_b32 v228, v203 offset:8
	ds_read_b32 v229, v203 offset:12
	ds_read_b32 v230, v203 offset:32
	ds_read_b32 v231, v203 offset:36
	ds_read_b32 v232, v203 offset:40
	ds_read_b32 v233, v203 offset:44
	ds_read_b32 v234, v203 offset:64
	ds_read_b32 v235, v203 offset:68
	ds_read_b32 v236, v203 offset:72
	ds_read_b32 v237, v203 offset:76
	ds_read_b32 v238, v203 offset:96
	ds_read_b32 v239, v203 offset:100
	ds_read_b32 v242, v203 offset:104
	ds_read_b32 v243, v203 offset:108
	ds_read_b32 v244, v203 offset:128
	ds_read_b32 v245, v203 offset:132
	ds_read_b32 v246, v203 offset:136
	ds_read_b32 v247, v203 offset:140
	s_waitcnt lgkmcnt(15)
	v_mfma_f32_32x32x16_bf16 v[34:49], v[82:85], v[66:69], 0
	ds_read_b128 v[82:85], v195 offset:8192
	v_mfma_f32_32x32x16_bf16 v[34:49], v[86:89], v[70:73], v[34:49]
	ds_read_b128 v[86:89], v195 offset:12288
	v_mfma_f32_32x32x16_bf16 v[34:49], v[90:93], v[74:77], v[34:49]
	ds_read_b128 v[90:93], v196 offset:8192
	v_mfma_f32_32x32x16_bf16 v[34:49], v[94:97], v[78:81], v[34:49]
	ds_read_b128 v[94:97], v196 offset:12288
	v_mfma_f32_32x32x16_bf16 v[50:65], v[98:101], v[66:69], 0
	ds_read_b128 v[98:101], v197 offset:8192
	v_mfma_f32_32x32x16_bf16 v[50:65], v[102:105], v[70:73], v[50:65]
	ds_read_b128 v[102:105], v197 offset:12288
	v_mfma_f32_32x32x16_bf16 v[50:65], v[106:109], v[74:77], v[50:65]
	v_mfma_f32_32x32x16_bf16 v[50:65], v[110:113], v[78:81], v[50:65]
	s_nop 7
	s_nop 3
	v_add_f32_e32 v34, v34, v226
	v_min_f32_e32 v34, v34, v206
	v_exp_f32_e32 v34, v34
	v_add_f32_e32 v35, v35, v227
	v_min_f32_e32 v35, v35, v207
	v_exp_f32_e32 v35, v35
	v_add_f32_e32 v36, v36, v228
	v_min_f32_e32 v36, v36, v208
	v_exp_f32_e32 v36, v36
	v_add_f32_e32 v37, v37, v229
	v_min_f32_e32 v37, v37, v209
	v_exp_f32_e32 v37, v37
	v_add_f32_e32 v38, v38, v230
	v_min_f32_e32 v38, v38, v210
	v_exp_f32_e32 v38, v38
	s_waitcnt lgkmcnt(15)
; DI float fast_exp2(float x) { return __builtin_amdgcn_exp2f(x); }
; template <bool NA, bool TRACK>
; DI void attn_item(char* lds, const bf16_t* P, bf16_t* Y, const bf16_t* vt, int rp, int q_off, int k1_off, int nt1,
;                   int vk1, int k2_off, int nt2, int vk2, int g_off, int y_off, int rlo, const float* rpb) {
;     ...
;         if (NA) {
;           if (t < nt1) {
;             const float* trow = tab + drow * 128 + 63 - cq;
; #pragma unroll
;             for (int kt = 0; kt < 2; ++kt)
; #pragma unroll
;               for (int i = 0; i < 16; ++i) {
;                 const int kc = kt * 32 + (i & 3) + 8 * (i >> 2) + 4 * h;
;                 const bool ok = (unsigned)(kc - c0) < 16u;
;                 const float t2 = s[kt][i] + trow[kc];
;                 s[kt][i] = ok ? t2 : -1e30f;
;               }
;           }
;         }
;         float mx = 0.f;
;         if (TRACK) {
;           mx = fmaxf(s[0][0], s[1][0]);
; #pragma unroll
;           for (int i = 1; i < 16; ++i) mx = fmaxf(fmaxf(mx, s[0][i]), s[1][i]);
;           mx = fmaxf(mx, __shfl_xor(mx, 32));
;         }
;         if (TRACK && __any(mx > 8.f)) {
;           const float dlt = fmaxf(mx, 0.f);
;           const float alpha = fast_exp2(-dlt);
;           l_run *= alpha;
; #pragma unroll
;           for (int i = 0; i < 16; ++i) { o[0][i] *= alpha; o[1][i] *= alpha; negm[i] -= dlt; }
; #pragma unroll
;           for (int i = 0; i < 16; ++i) { s[0][i] -= dlt; s[1][i] -= dlt; }
;         }
;         float ps = 0.f;
; #pragma unroll
;         for (int kt = 0; kt < 2; ++kt)
; #pragma unroll
;           for (int i = 0; i < 16; ++i) {
;             const float pv = fast_exp2(s[kt][i]);
;             ps += pv;
;             s[kt][i] = pv;
;           }
;         l_run += ps;
; #pragma unroll
;         for (int kt = 0; kt < 2; ++kt)
; #pragma unroll
;           for (int sp = 0; sp < 2; ++sp) {
;             u32x4 pu;
;             pu[0] = pk2(s[kt][8 * sp + 0], s[kt][8 * sp + 1]);
;             pu[1] = pk2(s[kt][8 * sp + 2], s[kt][8 * sp + 3]);
;             pu[2] = pk2(s[kt][8 * sp + 4], s[kt][8 * sp + 5]);
;             pu[3] = pk2(s[kt][8 * sp + 6], s[kt][8 * sp + 7]);
;             const bf16x8 pf = __builtin_bit_cast(bf16x8, pu);
; #pragma unroll
;             for (int dm = 0; dm < 2; ++dm) o[dm] = mfma32(vf[(kt * 2 + sp) * 2 + dm], pf, o[dm]);
;           }
	v_add_f32_e32 v39, v39, v231
	v_min_f32_e32 v39, v39, v211
	v_exp_f32_e32 v39, v39
	v_add_f32_e32 v40, v40, v232
	v_min_f32_e32 v40, v40, v212
	v_exp_f32_e32 v40, v40
	v_add_f32_e32 v41, v41, v233
	v_min_f32_e32 v41, v41, v213
	v_exp_f32_e32 v41, v41
	v_add_f32_e32 v42, v42, v234
	v_min_f32_e32 v42, v42, v214
	v_exp_f32_e32 v42, v42
	v_add_f32_e32 v43, v43, v235
	v_min_f32_e32 v43, v43, v215
	v_exp_f32_e32 v43, v43
	v_add_f32_e32 v44, v44, v236
	v_min_f32_e32 v44, v44, v216
	v_exp_f32_e32 v44, v44
	s_waitcnt lgkmcnt(14)
	v_add_f32_e32 v45, v45, v237
	v_min_f32_e32 v45, v45, v217
	v_exp_f32_e32 v45, v45
	s_waitcnt lgkmcnt(13)
	v_add_f32_e32 v46, v46, v238
	v_min_f32_e32 v46, v46, v218
	v_exp_f32_e32 v46, v46
	s_waitcnt lgkmcnt(12)
	v_add_f32_e32 v47, v47, v239
	v_min_f32_e32 v47, v47, v219
	v_exp_f32_e32 v47, v47
	s_waitcnt lgkmcnt(11)
	v_add_f32_e32 v48, v48, v242
	v_min_f32_e32 v48, v48, v220
	v_exp_f32_e32 v48, v48
	s_waitcnt lgkmcnt(10)
	v_add_f32_e32 v49, v49, v243
	v_min_f32_e32 v49, v49, v221
	v_exp_f32_e32 v49, v49
	s_waitcnt lgkmcnt(9)
	v_add_f32_e32 v50, v50, v244
	v_min_f32_e32 v50, v50, v222
	v_exp_f32_e32 v50, v50
	s_waitcnt lgkmcnt(8)
	v_add_f32_e32 v51, v51, v245
	v_min_f32_e32 v51, v51, v223
	v_exp_f32_e32 v51, v51
	s_waitcnt lgkmcnt(7)
	v_add_f32_e32 v52, v52, v246
	v_min_f32_e32 v52, v52, v224
	v_exp_f32_e32 v52, v52
	s_waitcnt lgkmcnt(6)
	v_add_f32_e32 v53, v53, v247
	v_min_f32_e32 v53, v53, v225
	v_exp_f32_e32 v53, v53
	s_nop 0
	v_add_f32_e32 v186, v186, v34
	v_add_f32_e32 v187, v187, v35
	v_cvt_pk_bf16_f32 v114, v34, v35
	v_add_f32_e32 v188, v188, v36
	v_add_f32_e32 v189, v189, v37
	v_cvt_pk_bf16_f32 v115, v36, v37
	v_add_f32_e32 v186, v186, v38
	v_add_f32_e32 v187, v187, v39
	v_cvt_pk_bf16_f32 v116, v38, v39
	v_add_f32_e32 v188, v188, v40
	v_add_f32_e32 v189, v189, v41
	v_cvt_pk_bf16_f32 v117, v40, v41
	v_add_f32_e32 v186, v186, v42
	v_add_f32_e32 v187, v187, v43
	v_cvt_pk_bf16_f32 v118, v42, v43
	v_add_f32_e32 v188, v188, v44
	v_add_f32_e32 v189, v189, v45
	v_cvt_pk_bf16_f32 v119, v44, v45
	v_add_f32_e32 v186, v186, v46
	v_add_f32_e32 v187, v187, v47
	v_cvt_pk_bf16_f32 v120, v46, v47
	v_add_f32_e32 v188, v188, v48
	v_add_f32_e32 v189, v189, v49
	v_cvt_pk_bf16_f32 v121, v48, v49
	v_add_f32_e32 v186, v186, v50
	v_add_f32_e32 v187, v187, v51
	v_cvt_pk_bf16_f32 v122, v50, v51
	v_add_f32_e32 v188, v188, v52
	v_add_f32_e32 v189, v189, v53
	v_cvt_pk_bf16_f32 v123, v52, v53
	s_nop 1
	s_waitcnt lgkmcnt(5)
	v_mfma_f32_32x32x16_bf16 v[18:33], v[82:85], v[114:117], v[18:33]
	s_waitcnt lgkmcnt(4)
	v_mfma_f32_32x32x16_bf16 v[2:17], v[86:89], v[114:117], v[2:17]
	s_waitcnt lgkmcnt(3)
	v_mfma_f32_32x32x16_bf16 v[18:33], v[90:93], v[118:121], v[18:33]
	s_waitcnt lgkmcnt(2)
	v_mfma_f32_32x32x16_bf16 v[2:17], v[94:97], v[118:121], v[2:17]
	s_waitcnt lgkmcnt(1)
	v_mfma_f32_32x32x16_bf16 v[18:33], v[98:101], v[122:125], v[18:33]
	s_waitcnt lgkmcnt(0)
	v_mfma_f32_32x32x16_bf16 v[2:17], v[102:105], v[122:125], v[2:17]
	s_branch .Lna_next
.Lna_t1:
	ds_read_b128 v[82:85], v195
	ds_read_b128 v[86:89], v196
	ds_read_b128 v[90:93], v197
	ds_read_b128 v[94:97], v198
	ds_read_b128 v[98:101], v195 offset:4096
	ds_read_b128 v[102:105], v196 offset:4096
	ds_read_b128 v[106:109], v197 offset:4096
	ds_read_b128 v[110:113], v198 offset:4096
	ds_read_b32 v226, v203 offset:96
	ds_read_b32 v227, v203 offset:100
	ds_read_b32 v228, v203 offset:104
	ds_read_b32 v229, v203 offset:108
	ds_read_b32 v230, v203 offset:128
	ds_read_b32 v231, v203 offset:132
	ds_read_b32 v232, v203 offset:136
	ds_read_b32 v233, v203 offset:140
	ds_read_b32 v234, v203 offset:160
	ds_read_b32 v235, v203 offset:164
	ds_read_b32 v236, v203 offset:168
	ds_read_b32 v237, v203 offset:172
	ds_read_b32 v238, v203 offset:192
	ds_read_b32 v239, v203 offset:196
	ds_read_b32 v242, v203 offset:200
	ds_read_b32 v243, v203 offset:204
	ds_read_b32 v244, v203 offset:224
	ds_read_b32 v245, v203 offset:228
	ds_read_b32 v246, v203 offset:232
	ds_read_b32 v247, v203 offset:236
	s_waitcnt lgkmcnt(15)
	v_mfma_f32_32x32x16_bf16 v[34:49], v[82:85], v[66:69], 0
	v_mfma_f32_32x32x16_bf16 v[34:49], v[86:89], v[70:73], v[34:49]
	v_mfma_f32_32x32x16_bf16 v[34:49], v[90:93], v[74:77], v[34:49]
	ds_read_b128 v[90:93], v196 offset:8192
	v_mfma_f32_32x32x16_bf16 v[34:49], v[94:97], v[78:81], v[34:49]
	ds_read_b128 v[94:97], v196 offset:12288
	v_mfma_f32_32x32x16_bf16 v[50:65], v[98:101], v[66:69], 0
	ds_read_b128 v[98:101], v197 offset:8192
	v_mfma_f32_32x32x16_bf16 v[50:65], v[102:105], v[70:73], v[50:65]
	ds_read_b128 v[102:105], v197 offset:12288
	v_mfma_f32_32x32x16_bf16 v[50:65], v[106:109], v[74:77], v[50:65]
	ds_read_b128 v[106:109], v198 offset:8192
	v_mfma_f32_32x32x16_bf16 v[50:65], v[110:113], v[78:81], v[50:65]
	ds_read_b128 v[110:113], v198 offset:12288
	s_nop 7
	s_nop 3
	v_add_f32_e32 v46, v46, v226
	v_min_f32_e32 v46, v46, v206
	v_exp_f32_e32 v46, v46
	v_add_f32_e32 v47, v47, v227
	v_min_f32_e32 v47, v47, v207
	v_exp_f32_e32 v47, v47
	v_add_f32_e32 v48, v48, v228
	v_min_f32_e32 v48, v48, v208
	v_exp_f32_e32 v48, v48
	v_add_f32_e32 v49, v49, v229
	v_min_f32_e32 v49, v49, v209
	v_exp_f32_e32 v49, v49
	v_add_f32_e32 v50, v50, v230
	v_min_f32_e32 v50, v50, v210
	v_exp_f32_e32 v50, v50
	s_waitcnt lgkmcnt(15)
	v_add_f32_e32 v51, v51, v231
	v_min_f32_e32 v51, v51, v211
	v_exp_f32_e32 v51, v51
	v_add_f32_e32 v52, v52, v232
	v_min_f32_e32 v52, v52, v212
	v_exp_f32_e32 v52, v52
	v_add_f32_e32 v53, v53, v233
	v_min_f32_e32 v53, v53, v213
	v_exp_f32_e32 v53, v53
	v_add_f32_e32 v54, v54, v234
	v_min_f32_e32 v54, v54, v214
	v_exp_f32_e32 v54, v54
	v_add_f32_e32 v55, v55, v235
	v_min_f32_e32 v55, v55, v215
	v_exp_f32_e32 v55, v55
	v_add_f32_e32 v56, v56, v236
	v_min_f32_e32 v56, v56, v216
	v_exp_f32_e32 v56, v56
	s_waitcnt lgkmcnt(14)
; DI f32x16 mfma32(bf16x8 a, bf16x8 b, f32x16 c) { return __builtin_amdgcn_mfma_f32_32x32x16_bf16(a, b, c, 0, 0, 0); }
; DI float fast_exp2(float x) { return __builtin_amdgcn_exp2f(x); }
; template <bool NA, bool TRACK>
; DI void attn_item(char* lds, const bf16_t* P, bf16_t* Y, const bf16_t* vt, int rp, int q_off, int k1_off, int nt1,
;                   int vk1, int k2_off, int nt2, int vk2, int g_off, int y_off, int rlo, const float* rpb) {
;     ...
;         float ps = 0.f;
; #pragma unroll
;         for (int kt = 0; kt < 2; ++kt)
; #pragma unroll
;           for (int i = 0; i < 16; ++i) {
;             const float pv = fast_exp2(s[kt][i]);
;             ps += pv;
;             s[kt][i] = pv;
;           }
;         l_run += ps;
; #pragma unroll
;         for (int kt = 0; kt < 2; ++kt)
; #pragma unroll
;           for (int sp = 0; sp < 2; ++sp) {
;             u32x4 pu;
;             pu[0] = pk2(s[kt][8 * sp + 0], s[kt][8 * sp + 1]);
;             pu[1] = pk2(s[kt][8 * sp + 2], s[kt][8 * sp + 3]);
;             pu[2] = pk2(s[kt][8 * sp + 4], s[kt][8 * sp + 5]);
;             pu[3] = pk2(s[kt][8 * sp + 6], s[kt][8 * sp + 7]);
;             const bf16x8 pf = __builtin_bit_cast(bf16x8, pu);
; #pragma unroll
;             for (int dm = 0; dm < 2; ++dm) o[dm] = mfma32(vf[(kt * 2 + sp) * 2 + dm], pf, o[dm]);
;           }
	v_add_f32_e32 v57, v57, v237
	v_min_f32_e32 v57, v57, v217
	v_exp_f32_e32 v57, v57
	s_waitcnt lgkmcnt(13)
	v_add_f32_e32 v58, v58, v238
	v_min_f32_e32 v58, v58, v218
	v_exp_f32_e32 v58, v58
	s_waitcnt lgkmcnt(12)
	v_add_f32_e32 v59, v59, v239
	v_min_f32_e32 v59, v59, v219
	v_exp_f32_e32 v59, v59
	s_waitcnt lgkmcnt(11)
	v_add_f32_e32 v60, v60, v242
	v_min_f32_e32 v60, v60, v220
	v_exp_f32_e32 v60, v60
	s_waitcnt lgkmcnt(10)
	v_add_f32_e32 v61, v61, v243
	v_min_f32_e32 v61, v61, v221
	v_exp_f32_e32 v61, v61
	s_waitcnt lgkmcnt(9)
	v_add_f32_e32 v62, v62, v244
	v_min_f32_e32 v62, v62, v222
	v_exp_f32_e32 v62, v62
	s_waitcnt lgkmcnt(8)
	v_add_f32_e32 v63, v63, v245
	v_min_f32_e32 v63, v63, v223
	v_exp_f32_e32 v63, v63
	s_waitcnt lgkmcnt(7)
	v_add_f32_e32 v64, v64, v246
	v_min_f32_e32 v64, v64, v224
	v_exp_f32_e32 v64, v64
	s_waitcnt lgkmcnt(6)
	v_add_f32_e32 v65, v65, v247
	v_min_f32_e32 v65, v65, v225
	v_exp_f32_e32 v65, v65
	s_nop 0
	v_add_f32_e32 v186, v186, v46
	v_add_f32_e32 v187, v187, v47
	v_cvt_pk_bf16_f32 v120, v46, v47
	v_add_f32_e32 v188, v188, v48
	v_add_f32_e32 v189, v189, v49
	v_cvt_pk_bf16_f32 v121, v48, v49
	v_add_f32_e32 v186, v186, v50
	v_add_f32_e32 v187, v187, v51
	v_cvt_pk_bf16_f32 v122, v50, v51
	v_add_f32_e32 v188, v188, v52
	v_add_f32_e32 v189, v189, v53
	v_cvt_pk_bf16_f32 v123, v52, v53
	v_add_f32_e32 v186, v186, v54
	v_add_f32_e32 v187, v187, v55
	v_cvt_pk_bf16_f32 v124, v54, v55
	v_add_f32_e32 v188, v188, v56
	v_add_f32_e32 v189, v189, v57
	v_cvt_pk_bf16_f32 v125, v56, v57
	v_add_f32_e32 v186, v186, v58
	v_add_f32_e32 v187, v187, v59
	v_cvt_pk_bf16_f32 v126, v58, v59
	v_add_f32_e32 v188, v188, v60
	v_add_f32_e32 v189, v189, v61
	v_cvt_pk_bf16_f32 v127, v60, v61
	v_add_f32_e32 v186, v186, v62
	v_add_f32_e32 v187, v187, v63
	v_cvt_pk_bf16_f32 v128, v62, v63
	v_add_f32_e32 v188, v188, v64
	v_add_f32_e32 v189, v189, v65
	v_cvt_pk_bf16_f32 v129, v64, v65
	s_nop 1
	s_waitcnt lgkmcnt(5)
	v_mfma_f32_32x32x16_bf16 v[18:33], v[90:93], v[118:121], v[18:33]
	s_waitcnt lgkmcnt(4)
	v_mfma_f32_32x32x16_bf16 v[2:17], v[94:97], v[118:121], v[2:17]
	s_waitcnt lgkmcnt(3)
	v_mfma_f32_32x32x16_bf16 v[18:33], v[98:101], v[122:125], v[18:33]
	s_waitcnt lgkmcnt(2)
	v_mfma_f32_32x32x16_bf16 v[2:17], v[102:105], v[122:125], v[2:17]
	s_waitcnt lgkmcnt(1)
	v_mfma_f32_32x32x16_bf16 v[18:33], v[106:109], v[126:129], v[18:33]
	s_waitcnt lgkmcnt(0)
	v_mfma_f32_32x32x16_bf16 v[2:17], v[110:113], v[126:129], v[2:17]
	s_branch .Lna_next
; DI f32x16 mfma32(bf16x8 a, bf16x8 b, f32x16 c) { return __builtin_amdgcn_mfma_f32_32x32x16_bf16(a, b, c, 0, 0, 0); }
; DI float fast_exp2(float x) { return __builtin_amdgcn_exp2f(x); }
; #define ATT_WRITE(IT, HALF) do { _Pragma("unroll") for (int j_ = 0; j_ < TPI; ++j_) { const int t_ = (IT) * TPI + j_; if (t_ < nt) { \
;       char* sl_ = lds + (HALF) * 65536 + j_ * 16384; \
;       *(u32x4*)(sl_ + woff) = rk[j_]; \
;       *(u32x4*)(sl_ + 8192 + woff) = rv[j_]; } } } while (0)
; template <bool NA, bool TRACK>
; DI void attn_item(char* lds, const bf16_t* P, bf16_t* Y, const bf16_t* vt, int rp, int q_off, int k1_off, int nt1,
;                   int vk1, int k2_off, int nt2, int vk2, int g_off, int y_off, int rlo, const float* rpb) {
;     ...
;         for (int kt = 0; kt < 2; ++kt)
; #pragma unroll
;           for (int ks = 0; ks < 4; ++ks)
;             kf[kt * 4 + ks] = *(const bf16x8*)(Ks + (kt * 32 + r) * 128 + (((2 * ks + h) ^ swz) << 4));
;         __builtin_amdgcn_sched_barrier(0);
;         f32x16 s[2];
;         __builtin_amdgcn_s_setprio(1);
; #pragma unroll
;         for (int kt = 0; kt < 2; ++kt) {
;           s[kt] = mfma32(kf[kt * 4], qf[0], negm);
; #pragma unroll
;           for (int ks = 1; ks < 4; ++ks) s[kt] = mfma32(kf[kt * 4 + ks], qf[ks], s[kt]);
;         }
;     ...
;         float ps = 0.f;
; #pragma unroll
;         for (int kt = 0; kt < 2; ++kt)
; #pragma unroll
;           for (int i = 0; i < 16; ++i) {
;             const float pv = fast_exp2(s[kt][i]);
;             ps += pv;
;             s[kt][i] = pv;
;           }
;         l_run += ps;
; #pragma unroll
;         for (int kt = 0; kt < 2; ++kt)
; #pragma unroll
;           for (int sp = 0; sp < 2; ++sp) {
;             u32x4 pu;
;             pu[0] = pk2(s[kt][8 * sp + 0], s[kt][8 * sp + 1]);
;             pu[1] = pk2(s[kt][8 * sp + 2], s[kt][8 * sp + 3]);
;             pu[2] = pk2(s[kt][8 * sp + 4], s[kt][8 * sp + 5]);
;             pu[3] = pk2(s[kt][8 * sp + 6], s[kt][8 * sp + 7]);
;             const bf16x8 pf = __builtin_bit_cast(bf16x8, pu);
; #pragma unroll
;             for (int dm = 0; dm < 2; ++dm) o[dm] = mfma32(vf[(kt * 2 + sp) * 2 + dm], pf, o[dm]);
;           }
;       }
;     }
;     if constexpr (NA || TRACK) { if (it + 1 < niter) ATT_WRITE(it + 1, hb ^ 1); }
;     __syncthreads();
;   }
.Lna_ctx:
	ds_read_b128 v[82:85], v195
	ds_read_b128 v[86:89], v196
	ds_read_b128 v[90:93], v197
	ds_read_b128 v[94:97], v198
	ds_read_b128 v[98:101], v195 offset:4096
	ds_read_b128 v[102:105], v196 offset:4096
	ds_read_b128 v[106:109], v197 offset:4096
	ds_read_b128 v[110:113], v198 offset:4096
	s_waitcnt lgkmcnt(7)
	v_mfma_f32_32x32x16_bf16 v[34:49], v[82:85], v[66:69], 0
	ds_read_b128 v[82:85], v195 offset:8192
	s_waitcnt lgkmcnt(7)
	v_mfma_f32_32x32x16_bf16 v[34:49], v[86:89], v[70:73], v[34:49]
	ds_read_b128 v[86:89], v195 offset:12288
	s_waitcnt lgkmcnt(7)
	v_mfma_f32_32x32x16_bf16 v[34:49], v[90:93], v[74:77], v[34:49]
	ds_read_b128 v[90:93], v196 offset:8192
	s_waitcnt lgkmcnt(7)
	v_mfma_f32_32x32x16_bf16 v[34:49], v[94:97], v[78:81], v[34:49]
	ds_read_b128 v[94:97], v196 offset:12288
	s_waitcnt lgkmcnt(7)
	v_mfma_f32_32x32x16_bf16 v[50:65], v[98:101], v[66:69], 0
	ds_read_b128 v[98:101], v197 offset:8192
	s_waitcnt lgkmcnt(7)
	v_mfma_f32_32x32x16_bf16 v[50:65], v[102:105], v[70:73], v[50:65]
	ds_read_b128 v[102:105], v197 offset:12288
	s_waitcnt lgkmcnt(7)
	v_mfma_f32_32x32x16_bf16 v[50:65], v[106:109], v[74:77], v[50:65]
	ds_read_b128 v[106:109], v198 offset:8192
	s_waitcnt lgkmcnt(7)
	v_mfma_f32_32x32x16_bf16 v[50:65], v[110:113], v[78:81], v[50:65]
	ds_read_b128 v[110:113], v198 offset:12288
	s_nop 7
	s_nop 3
	v_exp_f32_e32 v34, v34
	v_exp_f32_e32 v35, v35
	v_exp_f32_e32 v36, v36
	v_exp_f32_e32 v37, v37
	v_exp_f32_e32 v38, v38
	v_exp_f32_e32 v39, v39
	v_exp_f32_e32 v40, v40
	v_exp_f32_e32 v41, v41
	v_exp_f32_e32 v42, v42
	v_exp_f32_e32 v43, v43
	v_exp_f32_e32 v44, v44
	v_exp_f32_e32 v45, v45
	v_exp_f32_e32 v46, v46
	v_exp_f32_e32 v47, v47
	v_exp_f32_e32 v48, v48
	v_exp_f32_e32 v49, v49
	v_exp_f32_e32 v50, v50
	v_exp_f32_e32 v51, v51
	v_exp_f32_e32 v52, v52
	v_exp_f32_e32 v53, v53
	v_exp_f32_e32 v54, v54
	v_exp_f32_e32 v55, v55
	v_exp_f32_e32 v56, v56
	v_exp_f32_e32 v57, v57
	v_exp_f32_e32 v58, v58
	v_exp_f32_e32 v59, v59
	v_exp_f32_e32 v60, v60
	v_exp_f32_e32 v61, v61
	v_exp_f32_e32 v62, v62
	v_exp_f32_e32 v63, v63
	v_exp_f32_e32 v64, v64
	v_exp_f32_e32 v65, v65
	s_nop 0
	v_add_f32_e32 v186, v186, v34
	v_add_f32_e32 v187, v187, v35
	v_cvt_pk_bf16_f32 v114, v34, v35
	v_add_f32_e32 v188, v188, v36
	v_add_f32_e32 v189, v189, v37
	v_cvt_pk_bf16_f32 v115, v36, v37
	v_add_f32_e32 v186, v186, v38
	v_add_f32_e32 v187, v187, v39
	v_cvt_pk_bf16_f32 v116, v38, v39
	v_add_f32_e32 v188, v188, v40
	v_add_f32_e32 v189, v189, v41
	v_cvt_pk_bf16_f32 v117, v40, v41
	v_add_f32_e32 v186, v186, v42
	v_add_f32_e32 v187, v187, v43
	v_cvt_pk_bf16_f32 v118, v42, v43
	v_add_f32_e32 v188, v188, v44
	v_add_f32_e32 v189, v189, v45
	v_cvt_pk_bf16_f32 v119, v44, v45
	v_add_f32_e32 v186, v186, v46
	v_add_f32_e32 v187, v187, v47
	v_cvt_pk_bf16_f32 v120, v46, v47
	v_add_f32_e32 v188, v188, v48
	v_add_f32_e32 v189, v189, v49
	v_cvt_pk_bf16_f32 v121, v48, v49
	v_add_f32_e32 v186, v186, v50
	v_add_f32_e32 v187, v187, v51
	v_cvt_pk_bf16_f32 v122, v50, v51
	v_add_f32_e32 v188, v188, v52
	v_add_f32_e32 v189, v189, v53
	v_cvt_pk_bf16_f32 v123, v52, v53
	v_add_f32_e32 v186, v186, v54
	v_add_f32_e32 v187, v187, v55
	v_cvt_pk_bf16_f32 v124, v54, v55
	v_add_f32_e32 v188, v188, v56
	v_add_f32_e32 v189, v189, v57
	v_cvt_pk_bf16_f32 v125, v56, v57
	v_add_f32_e32 v186, v186, v58
	v_add_f32_e32 v187, v187, v59
	v_cvt_pk_bf16_f32 v126, v58, v59
	v_add_f32_e32 v188, v188, v60
	v_add_f32_e32 v189, v189, v61
	v_cvt_pk_bf16_f32 v127, v60, v61
	v_add_f32_e32 v186, v186, v62
	v_add_f32_e32 v187, v187, v63
	v_cvt_pk_bf16_f32 v128, v62, v63
	v_add_f32_e32 v188, v188, v64
	v_add_f32_e32 v189, v189, v65
	v_cvt_pk_bf16_f32 v129, v64, v65
	s_nop 1
	s_waitcnt lgkmcnt(7)
	v_mfma_f32_32x32x16_bf16 v[18:33], v[82:85], v[114:117], v[18:33]
	s_waitcnt lgkmcnt(6)
	v_mfma_f32_32x32x16_bf16 v[2:17], v[86:89], v[114:117], v[2:17]
	s_waitcnt lgkmcnt(5)
	v_mfma_f32_32x32x16_bf16 v[18:33], v[90:93], v[118:121], v[18:33]
	s_waitcnt lgkmcnt(4)
	v_mfma_f32_32x32x16_bf16 v[2:17], v[94:97], v[118:121], v[2:17]
	s_waitcnt lgkmcnt(3)
	v_mfma_f32_32x32x16_bf16 v[18:33], v[98:101], v[122:125], v[18:33]
	s_waitcnt lgkmcnt(2)
	v_mfma_f32_32x32x16_bf16 v[2:17], v[102:105], v[122:125], v[2:17]
	s_waitcnt lgkmcnt(1)
	v_mfma_f32_32x32x16_bf16 v[18:33], v[106:109], v[126:129], v[18:33]
	s_waitcnt lgkmcnt(0)
	v_mfma_f32_32x32x16_bf16 v[2:17], v[110:113], v[126:129], v[2:17]
.Lna_next:
	s_add_i32 s31, s31, 1
	s_addk_i32 s42, 0x4000
	s_cmp_lt_i32 s31, s41
	s_cbranch_scc1 .Lna_tile
	s_waitcnt vmcnt(0)
	s_lshl_b32 s31, s18, 2
	s_add_i32 s31, s31, 4
	s_cmp_ge_i32 s31, s30
	s_cbranch_scc1 .Lna_wr0
	ds_write_b128 v199, v[130:133]
	ds_write_b128 v199, v[134:137] offset:8192
.Lna_wr0:
	s_lshl_b32 s31, s18, 2
	s_add_i32 s31, s31, 5
	s_cmp_ge_i32 s31, s30
	s_cbranch_scc1 .Lna_wr1
	ds_write_b128 v199, v[138:141] offset:16384
	ds_write_b128 v199, v[142:145] offset:24576
.Lna_wr1:
	s_lshl_b32 s31, s18, 2
	s_add_i32 s31, s31, 6
	s_cmp_ge_i32 s31, s30
	s_cbranch_scc1 .Lna_wr2
	ds_write_b128 v199, v[146:149] offset:32768
	ds_write_b128 v199, v[150:153] offset:40960
.Lna_wr2:
	s_lshl_b32 s31, s18, 2
	s_add_i32 s31, s31, 7
	s_cmp_ge_i32 s31, s30
	s_cbranch_scc1 .Lna_wr3
	ds_write_b128 v199, v[154:157] offset:49152
	ds_write_b128 v199, v[158:161] offset:57344
.Lna_wr3:
	s_waitcnt lgkmcnt(0)
	s_barrier
	v_xor_b32_e32 v191, 0x10000, v191
	v_xor_b32_e32 v192, 0x10000, v192
	v_xor_b32_e32 v193, 0x10000, v193
	v_xor_b32_e32 v194, 0x10000, v194
	v_xor_b32_e32 v199, 0x10000, v199
	s_add_i32 s18, s18, 1
	s_cmp_lt_i32 s18, s19
	s_cbranch_scc1 .Lna_loop
	v_add_f32_e32 v186, v186, v187
	v_add_f32_e32 v188, v188, v189
	s_nop 0
	v_add_f32_e32 v34, v186, v188
	s_branch .LBB0_80
